# attention loop diet + scan MFMA stage: 32 ER/EB address ORs per chunk folded into ds_read immediate offsets
# speedup vs baseline: 1.0095x; 1.0095x over previous
.LBB0_391:
	s_andn2_b64 vcc, exec, s[0:1]
	s_cbranch_vccnz .LBB0_471
	v_readlane_b32 s0, v252, 25
	v_mov_b32_e32 v115, v228
	v_readlane_b32 s1, v252, 26
	s_andn2_b64 vcc, exec, s[0:1]
	v_readfirstlane_b32 s0, v115
	s_cbranch_vccnz .LBB0_416
	s_ashr_i32 s2, s0, 6
	v_bfe_u32 v7, v115, 4, 2
	v_lshl_or_b32 v130, s2, 2, v7
	s_cmp_lt_i32 s2, 4
	v_cmp_lt_i32_e32 vcc, s33, v130
	s_cselect_b64 s[40:41], -1, 0
	s_lshl_b32 s3, s2, 4
	v_cndmask_b32_e32 v7, v207, v208, vcc
	s_cmp_lt_i32 s2, 2
	v_sub_u32_e32 v131, v7, v130
	v_bfe_u32 v7, v115, 3, 3
	s_cselect_b64 s[14:15], -1, 0
	s_cmp_gt_i32 s2, 1
	v_and_b32_e32 v4, 31, v115
	s_mul_i32 s26, s2, 0x410
	v_lshl_or_b32 v132, s2, 3, v7
	s_mul_i32 s6, s2, 0x420
	s_cselect_b64 s[12:13], -1, 0
	s_lshl_b32 s8, s2, 5
	s_lshl_b32 s7, s2, 12
	s_add_i32 s10, s2, -2
	s_lshl_b32 s2, s2, 11
	v_ashrrev_i32_e32 v1, 2, v115
	v_and_b32_e32 v0, 63, v115
	v_lshlrev_b32_e32 v11, 6, v4
	s_add_i32 s2, s2, 0x10400
	v_lshlrev_b32_e32 v128, 1, v1
	v_lshl_or_b32 v129, v0, 2, v206
	v_and_b32_e32 v0, 0x7ffffff0, v1
	v_cmp_lt_i32_e32 vcc, s33, v132
	v_lshlrev_b32_e32 v138, 8, v4
	v_add_u32_e32 v140, s2, v11
	s_movk_i32 s2, 0xff40
	v_and_or_b32 v5, v128, 8, v0
	v_and_b32_e32 v6, 3, v115
	v_cndmask_b32_e32 v7, v207, v208, vcc
	v_mad_i32_i24 v142, v4, s2, v138
	s_movk_i32 s2, 0x11ff
	v_sub_u32_e32 v133, v7, v132
	v_lshlrev_b32_e32 v7, 3, v6
	v_lshrrev_b32_e32 v5, 3, v5
	v_bitop3_b32 v144, v4, s2, v209 bitop3:0x36
	s_movk_i32 s2, 0x820
	v_cmp_eq_u32_e64 s[0:1], 0, v6
	v_cmp_lt_u32_e64 s[38:39], 1, v6
	v_and_b32_e32 v8, 8, v1
	v_mul_u32_u24_e32 v137, 0x420, v6
	s_lshl_b32 s11, s10, 11
	v_mad_u32_u24 v145, v6, s2, v128
	v_lshlrev_b32_e32 v6, 11, v6
	v_bitop3_b32 v21, v5, v7, 8 bitop3:0x78
	v_and_or_b32 v8, v128, 6, v8
	s_add_i32 s11, s11, 0x10400
	v_or_b32_e32 v14, 4, v7
	v_lshl_add_u32 v6, v21, 4, v6
	v_bfe_u32 v3, v115, 5, 1
	v_add_u32_e32 v12, s11, v11
	v_lshrrev_b32_e32 v15, 2, v14
	s_movk_i32 s2, 0x410
	v_or_b32_e32 v147, v6, v8
	v_or_b32_e32 v6, 1, v7
	v_lshl_or_b32 v139, v3, 3, v12
	v_or_b32_e32 v11, 2, v7
	v_or_b32_e32 v12, 3, v7
	v_mad_u32_u24 v146, v15, s2, v128
	v_or_b32_e32 v15, 5, v7
	v_or_b32_e32 v17, 6, v7
	v_or_b32_e32 v19, 7, v7
	v_lshlrev_b32_e32 v7, 8, v6
	v_bitop3_b32 v6, v5, v6, 9 bitop3:0x78
	v_lshl_add_u32 v6, v6, 4, v7
	v_or_b32_e32 v148, v6, v8
	v_lshlrev_b32_e32 v6, 8, v11
	v_bitop3_b32 v7, v5, v11, 10 bitop3:0x78
	v_lshl_add_u32 v6, v7, 4, v6
	v_or_b32_e32 v149, v6, v8
	v_lshlrev_b32_e32 v6, 8, v12
	v_bitop3_b32 v7, v5, v12, 11 bitop3:0x78
	v_lshl_add_u32 v6, v7, 4, v6
	v_or_b32_e32 v150, v6, v8
	v_lshlrev_b32_e32 v6, 8, v14
	v_bitop3_b32 v7, v5, v14, 12 bitop3:0x78
	v_lshl_add_u32 v6, v7, 4, v6
	v_or_b32_e32 v151, v6, v8
	v_lshlrev_b32_e32 v6, 8, v15
	v_bitop3_b32 v7, v5, v15, 13 bitop3:0x78
	v_lshl_add_u32 v6, v7, 4, v6
	v_or_b32_e32 v152, v6, v8
	v_lshlrev_b32_e32 v6, 8, v17
	v_bitop3_b32 v7, v5, v17, 14 bitop3:0x78
	v_lshl_add_u32 v6, v7, 4, v6
	v_or_b32_e32 v153, v6, v8
	v_lshlrev_b32_e32 v6, 8, v19
	v_bitop3_b32 v5, v5, v19, 15 bitop3:0x78
	v_lshl_add_u32 v5, v5, 4, v6
	v_lshlrev_b32_e32 v114, 2, v3
	v_and_b32_e32 v13, 15, v115
	v_or_b32_e32 v154, v5, v8
	v_bitop3_b32 v5, v3, v115, 15 bitop3:0x78
	v_lshlrev_b32_e32 v155, 4, v5
	v_bitop3_b32 v5, v3, v13, 2 bitop3:0x36
	v_or_b32_e32 v8, 3, v114
	v_or_b32_e32 v11, 2, v114
	v_lshlrev_b32_e32 v156, 4, v5
	v_bitop3_b32 v5, v3, v13, 4 bitop3:0x36
	v_cmp_gt_u32_e64 s[48:49], v8, v4
	v_cmp_gt_u32_e64 s[50:51], v11, v4
	v_or_b32_e32 v8, 9, v114
	v_or_b32_e32 v11, 8, v114
	v_lshlrev_b32_e32 v157, 4, v5
	v_bitop3_b32 v5, v3, v13, 6 bitop3:0x36
	v_cmp_gt_u32_e64 s[52:53], v8, v4
	v_cmp_gt_u32_e64 s[54:55], v11, v4
	v_or_b32_e32 v8, 11, v114
	v_or_b32_e32 v11, 10, v114
	v_lshlrev_b32_e32 v158, 4, v5
	v_bitop3_b32 v5, v3, v13, 8 bitop3:0x36
	v_cmp_gt_u32_e64 s[56:57], v8, v4
	v_cmp_gt_u32_e64 s[58:59], v11, v4
	v_or_b32_e32 v8, 17, v114
	v_or_b32_e32 v11, 16, v114
	v_lshlrev_b32_e32 v159, 4, v5
	v_bitop3_b32 v5, v3, v13, 10 bitop3:0x36
	v_cmp_gt_u32_e64 s[60:61], v8, v4
	v_cmp_gt_u32_e64 s[62:63], v11, v4
	v_or_b32_e32 v8, 19, v114
	v_or_b32_e32 v11, 18, v114
	v_lshlrev_b32_e32 v2, 3, v115
	v_bfe_u32 v10, v115, 2, 2
	v_lshlrev_b32_e32 v160, 4, v5
	v_bitop3_b32 v5, v3, v13, 12 bitop3:0x36
	v_cmp_gt_u32_e64 s[64:65], v8, v4
	v_cmp_gt_u32_e64 s[66:67], v11, v4
	v_or_b32_e32 v8, 25, v114
	v_or_b32_e32 v11, 24, v114
	v_and_b32_e32 v0, 0x78, v2
	v_lshlrev_b32_e32 v135, 6, v1
	v_lshlrev_b32_e32 v1, 4, v115
	v_lshrrev_b32_e32 v9, 2, v115
	v_lshrrev_b32_e32 v16, 2, v15
	v_lshrrev_b32_e32 v18, 2, v17
	v_lshrrev_b32_e32 v20, 2, v19
	v_lshlrev_b32_e32 v161, 4, v5
	v_bitop3_b32 v5, v3, v13, 14 bitop3:0x36
	v_lshlrev_b32_e32 v163, 4, v10
	v_cmp_gt_u32_e64 s[68:69], v8, v4
	v_cmp_gt_u32_e64 s[70:71], v11, v4
	v_or_b32_e32 v8, 27, v114
	v_or_b32_e32 v11, 26, v114
	v_lshlrev_b32_e32 v176, 1, v0
	v_and_b32_e32 v2, 56, v2
	v_or_b32_e32 v134, 0xffffffe0, v115
	v_bitop3_b32 v136, v1, 48, v115 bitop3:0x48
	v_add_u32_e32 v1, 0x10400, v135
	v_lshlrev_b32_e32 v141, 4, v3
	v_or_b32_e32 v254, 0x11400, v141
	v_or_b32_e32 v143, 0x10e0, v4
	v_lshlrev_b32_e32 v162, 4, v5
	v_xor_b32_e32 v5, 16, v163
	v_xor_b32_e32 v6, 32, v163
	v_xor_b32_e32 v7, 48, v163
	v_cmp_gt_u32_e64 s[44:45], v114, v4
	v_cmp_lt_u32_e64 s[46:47], v114, v4
	v_cmp_gt_u32_e64 s[72:73], v8, v4
	v_cmp_gt_u32_e64 s[74:75], v11, v4
	v_bitop3_b32 v4, v3, v9, 3 bitop3:0x78
	v_bitop3_b32 v3, v3, v10, 2 bitop3:0x36
	v_mad_u32_u24 v166, v16, s2, v128
	v_mad_u32_u24 v167, v18, s2, v128
	v_mad_u32_u24 v168, v20, s2, v128
	s_add_i32 s88, s26, s3
	v_readlane_b32 s2, v252, 52
	v_lshl_add_u64 v[112:113], s[86:87], 0, v[176:177]
	v_cmp_gt_i32_e64 s[42:43], s27, v115
	s_ashr_i32 s9, s8, 31
	s_lshl_b32 s10, s10, 12
	v_lshlrev_b32_e32 v164, 4, v4
	v_lshlrev_b32_e32 v165, 4, v3
	v_sub_u32_e32 v169, 0, v134
	v_add_u32_e32 v170, 32, v132
	v_sub_u32_e32 v171, 0xffffffe0, v132
	v_add_u32_e32 v172, 32, v130
	v_sub_u32_e32 v173, 0xffffffe0, v130
	v_lshlrev_b32_e32 v176, 1, v0
	v_lshlrev_b32_e32 v116, 1, v2
	s_add_i32 s11, s26, 0x2080
	s_addk_i32 s88, 0x4100
	v_add_u32_e32 v174, v1, v136
	v_add_u32_e32 v175, v139, v5
	v_add_u32_e32 v178, v139, v6
	v_add_u32_e32 v179, v139, v7
	s_mov_b32 s89, s2
	v_readlane_b32 s3, v252, 53
	s_branch .LBB0_395

.LBB0_412:
	s_andn2_b64 vcc, exec, s[20:21]
	s_cbranch_vccnz .LBB0_398
	v_add_u32_e32 v64, v138, v155
	v_add_u32_e32 v68, v138, v156
	ds_read_b128 v[64:67], v64 offset:41984
	ds_read_b128 v[80:83], v68 offset:41984
	ds_read_b128 v[68:71], v254
	ds_read_b128 v[72:75], v254 offset:32
	ds_read_b128 v[76:79], v254 offset:64
	ds_read_b128 v[84:87], v254 offset:96
	s_waitcnt lgkmcnt(3)
	v_pk_mul_f32 v[68:69], v[0:1], v[68:69]
	v_pk_mul_f32 v[70:71], v[2:3], v[70:71]
	v_cvt_pk_bf16_f32 v68, v68, v69
	v_cvt_pk_bf16_f32 v69, v70, v71
	s_waitcnt lgkmcnt(2)
	v_pk_mul_f32 v[70:71], v[4:5], v[72:73]
	v_pk_mul_f32 v[72:73], v[6:7], v[74:75]
	s_waitcnt lgkmcnt(0)
	v_pk_mul_f32 v[84:85], v[12:13], v[84:85]
	v_cvt_pk_bf16_f32 v70, v70, v71
	v_cvt_pk_bf16_f32 v71, v72, v73
	v_cvt_pk_bf16_f32 v90, v84, v85
	v_pk_mul_f32 v[84:85], v[14:15], v[86:87]
	v_pk_mul_f32 v[72:73], v[8:9], v[76:77]
	v_cvt_pk_bf16_f32 v91, v84, v85
	v_add_u32_e32 v84, v138, v157
	v_add_u32_e32 v85, v138, v158
	ds_read_b128 v[96:99], v84 offset:41984
	ds_read_b128 v[100:103], v85 offset:41984
	ds_read_b128 v[104:107], v254 offset:128
	ds_read_b128 v[108:111], v254 offset:160
	v_cvt_pk_bf16_f32 v88, v72, v73
	v_pk_mul_f32 v[72:73], v[10:11], v[78:79]
	v_cvt_pk_bf16_f32 v89, v72, v73
	v_mfma_f32_32x32x16_bf16 v[64:79], v[68:71], v[64:67], 0
	s_waitcnt lgkmcnt(1)
	v_mul_f32_e64 v104, v16, v104
	v_mul_f32_e64 v105, v17, v105
	v_mul_f32_e64 v106, v18, v106
	v_mul_f32_e64 v107, v19, v107
	v_cvt_pk_bf16_f32 v104, v104, v105
	v_cvt_pk_bf16_f32 v105, v106, v107
	s_waitcnt lgkmcnt(0)
	v_pk_mul_f32 v[106:107], v[20:21], v[108:109]
	v_pk_mul_f32 v[108:109], v[22:23], v[110:111]
	ds_read_b128 v[182:185], v254 offset:192
	ds_read_b128 v[186:189], v254 offset:224
	v_cvt_pk_bf16_f32 v106, v106, v107
	v_cvt_pk_bf16_f32 v107, v108, v109
	v_mfma_f32_32x32x16_bf16 v[80:95], v[88:91], v[80:83], 0
	s_waitcnt lgkmcnt(1)
	v_mul_f32_e64 v108, v24, v182
	v_mul_f32_e64 v109, v25, v183
	v_mul_f32_e64 v110, v26, v184
	v_mul_f32_e64 v111, v27, v185
	v_cvt_pk_bf16_f32 v108, v108, v109
	v_cvt_pk_bf16_f32 v109, v110, v111
	s_waitcnt lgkmcnt(0)
	v_pk_mul_f32 v[110:111], v[28:29], v[186:187]
	v_cvt_pk_bf16_f32 v110, v110, v111
	v_mfma_f32_32x32x16_bf16 v[64:79], v[104:107], v[96:99], v[64:79]
	v_mul_f32_e64 v96, v30, v188
	v_mul_f32_e64 v97, v31, v189
	v_add_u32_e32 v104, v138, v160
	v_cvt_pk_bf16_f32 v111, v96, v97
	v_add_u32_e32 v96, v138, v159
	ds_read_b128 v[96:99], v96 offset:41984
	ds_read_b128 v[104:107], v104 offset:41984
	v_add_u32_e32 v198, v140, v164
	v_mfma_f32_32x32x16_bf16 v[80:95], v[108:111], v[100:103], v[80:95]
	ds_read_b128 v[100:103], v254 offset:256
	ds_read_b128 v[108:111], v254 offset:288
	ds_read_b128 v[182:185], v254 offset:320
	ds_read_b128 v[186:189], v254 offset:352
	v_add_u32_e32 v212, v140, v165
	s_waitcnt lgkmcnt(3)
	v_pk_mul_f32 v[100:101], v[32:33], v[100:101]
	v_pk_mul_f32 v[102:103], v[34:35], v[102:103]
	v_cvt_pk_bf16_f32 v100, v100, v101
	v_cvt_pk_bf16_f32 v101, v102, v103
	s_waitcnt lgkmcnt(2)
	v_pk_mul_f32 v[102:103], v[36:37], v[108:109]
	v_pk_mul_f32 v[108:109], v[38:39], v[110:111]
	v_cvt_pk_bf16_f32 v102, v102, v103
	v_cvt_pk_bf16_f32 v103, v108, v109
	s_waitcnt lgkmcnt(1)
	v_pk_mul_f32 v[108:109], v[40:41], v[182:183]
	v_pk_mul_f32 v[110:111], v[42:43], v[184:185]
	v_cvt_pk_bf16_f32 v108, v108, v109
	v_cvt_pk_bf16_f32 v109, v110, v111
	s_waitcnt lgkmcnt(0)
	v_pk_mul_f32 v[110:111], v[44:45], v[186:187]
	v_mfma_f32_32x32x16_bf16 v[64:79], v[100:103], v[96:99], v[64:79]
	v_mul_f32_e64 v96, v46, v188
	v_mul_f32_e64 v97, v47, v189
	v_cvt_pk_bf16_f32 v110, v110, v111
	v_cvt_pk_bf16_f32 v111, v96, v97
	v_add_u32_e32 v96, v138, v161
	v_add_u32_e32 v100, v138, v162
	ds_read_b128 v[96:99], v96 offset:41984
	ds_read_b128 v[100:103], v100 offset:41984
	v_mfma_f32_32x32x16_bf16 v[80:95], v[108:111], v[104:107], v[80:95]
	ds_read_b128 v[104:107], v254 offset:384
	ds_read_b128 v[108:111], v254 offset:416
	ds_read_b128 v[182:185], v254 offset:448
	ds_read_b128 v[186:189], v254 offset:480
	v_add_u32_e32 v181, v142, v164
	s_waitcnt lgkmcnt(3)
	v_pk_mul_f32 v[104:105], v[48:49], v[104:105]
	v_pk_mul_f32 v[106:107], v[50:51], v[106:107]
	v_cvt_pk_bf16_f32 v104, v104, v105
	v_cvt_pk_bf16_f32 v105, v106, v107
	s_waitcnt lgkmcnt(2)
	v_pk_mul_f32 v[106:107], v[52:53], v[108:109]
	v_pk_mul_f32 v[108:109], v[54:55], v[110:111]
	v_cvt_pk_bf16_f32 v106, v106, v107
	v_cvt_pk_bf16_f32 v107, v108, v109
	s_waitcnt lgkmcnt(1)
	v_pk_mul_f32 v[108:109], v[56:57], v[182:183]
	v_pk_mul_f32 v[110:111], v[58:59], v[184:185]
	v_cvt_pk_bf16_f32 v108, v108, v109
	v_cvt_pk_bf16_f32 v109, v110, v111
	s_waitcnt lgkmcnt(0)
	v_pk_mul_f32 v[110:111], v[60:61], v[186:187]
	v_mfma_f32_32x32x16_bf16 v[64:79], v[104:107], v[96:99], v[64:79]
	v_mul_f32_e64 v96, v62, v188
	v_mul_f32_e64 v97, v63, v189
	v_cvt_pk_bf16_f32 v110, v110, v111
	v_cvt_pk_bf16_f32 v111, v96, v97
	v_add_u32_e32 v211, v142, v165
	s_nop 0
	v_mfma_f32_32x32x16_bf16 v[80:95], v[108:111], v[100:103], v[80:95]
	ds_read_b128 v[96:99], v181 offset:58368
	ds_read_b128 v[100:103], v181 offset:60416
	ds_read_b128 v[104:107], v211 offset:58368
	ds_read_b128 v[108:111], v211 offset:60416
	ds_read_b128 v[182:185], v254 offset:576
	ds_read_b128 v[186:189], v254 offset:608
	ds_read_b128 v[190:193], v254 offset:512
	ds_read_b128 v[194:197], v254 offset:544
	ds_read_b128 v[198:201], v198
	ds_read_b128 v[212:215], v212
	s_waitcnt lgkmcnt(4)
	v_pk_mul_f32 v[12:13], v[12:13], v[186:187]
	v_pk_mul_f32 v[8:9], v[8:9], v[182:183]
	s_waitcnt lgkmcnt(2)
	v_pk_mul_f32 v[4:5], v[4:5], v[194:195]
	v_pk_mul_f32 v[14:15], v[14:15], v[188:189]
	v_pk_mul_f32 v[10:11], v[10:11], v[184:185]
	v_pk_mul_f32 v[6:7], v[6:7], v[196:197]
	v_pk_mul_f32 v[2:3], v[2:3], v[192:193]
	v_pk_mul_f32 v[0:1], v[0:1], v[190:191]
	s_waitcnt lgkmcnt(1)
	s_nop 0
	v_mfma_f32_32x32x16_bf16 v[0:15], v[96:99], v[198:201], v[0:15]
	ds_read_b128 v[96:99], v254 offset:704
	ds_read_b128 v[182:185], v254 offset:736
	ds_read_b128 v[186:189], v254 offset:640
	ds_read_b128 v[190:193], v254 offset:672
	ds_read_b128 v[194:197], v211 offset:62464
	s_waitcnt lgkmcnt(4)
	v_pk_mul_f32 v[24:25], v[24:25], v[96:97]
	s_waitcnt lgkmcnt(3)
	v_pk_mul_f32 v[28:29], v[28:29], v[182:183]
	v_pk_mul_f32 v[30:31], v[30:31], v[184:185]
	s_waitcnt lgkmcnt(1)
	v_pk_mul_f32 v[20:21], v[20:21], v[190:191]
	v_pk_mul_f32 v[26:27], v[26:27], v[98:99]
	v_pk_mul_f32 v[22:23], v[22:23], v[192:193]
	v_pk_mul_f32 v[18:19], v[18:19], v[188:189]
	v_pk_mul_f32 v[16:17], v[16:17], v[186:187]
	v_mfma_f32_32x32x16_bf16 v[0:15], v[104:107], v[212:215], v[0:15]
	v_add_f32_e64 v78, v78, v94
	v_add_f32_e64 v79, v79, v95
	v_pk_add_f32 v[76:77], v[76:77], v[92:93]
	v_pk_add_f32 v[74:75], v[74:75], v[90:91]
	v_pk_add_f32 v[72:73], v[72:73], v[88:89]
	v_mfma_f32_32x32x16_bf16 v[16:31], v[100:103], v[198:201], v[16:31]
	ds_read_b128 v[96:99], v254 offset:832
	ds_read_b128 v[100:103], v254 offset:864
	ds_read_b128 v[104:107], v254 offset:768
	ds_read_b128 v[182:185], v254 offset:800
	ds_read_b128 v[186:189], v181 offset:62464
	ds_read_b128 v[190:193], v181 offset:64512
	s_waitcnt lgkmcnt(4)
	v_pk_mul_f32 v[44:45], v[44:45], v[100:101]
	v_pk_mul_f32 v[40:41], v[40:41], v[96:97]
	s_waitcnt lgkmcnt(3)
	v_pk_mul_f32 v[32:33], v[32:33], v[104:105]
	v_mfma_f32_32x32x16_bf16 v[16:31], v[108:111], v[212:215], v[16:31]
	s_waitcnt lgkmcnt(2)
	v_mul_f32_e64 v36, v36, v182
	v_mul_f32_e64 v37, v37, v183
	v_pk_mul_f32 v[46:47], v[46:47], v[102:103]
	v_pk_mul_f32 v[42:43], v[42:43], v[98:99]
	v_pk_mul_f32 v[38:39], v[38:39], v[184:185]
	v_pk_mul_f32 v[34:35], v[34:35], v[106:107]
	ds_read_b128 v[96:99], v254 offset:960
	ds_read_b128 v[100:103], v254 offset:992
	ds_read_b128 v[104:107], v254 offset:896
	ds_read_b128 v[108:111], v254 offset:928
	ds_read_b128 v[182:185], v211 offset:64512
	s_waitcnt lgkmcnt(4)
	v_pk_mul_f32 v[56:57], v[56:57], v[96:97]
	s_waitcnt lgkmcnt(3)
	v_pk_mul_f32 v[60:61], v[60:61], v[100:101]
	v_pk_mul_f32 v[62:63], v[62:63], v[102:103]
	s_waitcnt lgkmcnt(1)
	v_pk_mul_f32 v[52:53], v[52:53], v[108:109]
	v_pk_mul_f32 v[58:59], v[58:59], v[98:99]
	v_pk_mul_f32 v[54:55], v[54:55], v[110:111]
	v_pk_mul_f32 v[50:51], v[50:51], v[106:107]
	v_pk_mul_f32 v[48:49], v[48:49], v[104:105]
	v_mfma_f32_32x32x16_bf16 v[32:47], v[186:189], v[198:201], v[32:47]
	v_add_f32_e64 v70, v70, v86
	v_add_f32_e64 v71, v71, v87
	v_add_f32_e64 v68, v68, v84
	v_add_f32_e64 v69, v69, v85
	v_add_f32_e64 v66, v66, v82
	v_add_f32_e64 v67, v67, v83
	v_pk_add_f32 v[64:65], v[64:65], v[80:81]
	v_mfma_f32_32x32x16_bf16 v[48:63], v[190:193], v[198:201], v[48:63]
	v_mfma_f32_32x32x16_bf16 v[32:47], v[194:197], v[212:215], v[32:47]
	s_waitcnt lgkmcnt(0)
	v_mfma_f32_32x32x16_bf16 v[48:63], v[182:185], v[212:215], v[48:63]
	s_branch .LBB0_398

	.amdhsa_kernel _Z14fwd_megakernel6Params
		.amdhsa_group_segment_fixed_size 147472
		.amdhsa_private_segment_fixed_size 0
		.amdhsa_kernarg_size 432
		.amdhsa_user_sgpr_count 2
		.amdhsa_user_sgpr_dispatch_ptr 0
		.amdhsa_user_sgpr_queue_ptr 0
		.amdhsa_user_sgpr_kernarg_segment_ptr 1
		.amdhsa_user_sgpr_dispatch_id 0
		.amdhsa_user_sgpr_kernarg_preload_length 0
		.amdhsa_user_sgpr_kernarg_preload_offset 0
		.amdhsa_user_sgpr_private_segment_size 0
		.amdhsa_uses_dynamic_stack 0
		.amdhsa_enable_private_segment 0
		.amdhsa_system_sgpr_workgroup_id_x 1
		.amdhsa_system_sgpr_workgroup_id_y 0
		.amdhsa_system_sgpr_workgroup_id_z 0
		.amdhsa_system_sgpr_workgroup_info 0
		.amdhsa_system_vgpr_workitem_id 2
		.amdhsa_next_free_vgpr 255
		.amdhsa_next_free_sgpr 102
		.amdhsa_accum_offset 256
		.amdhsa_reserve_vcc 1
		.amdhsa_float_round_mode_32 0
		.amdhsa_float_round_mode_16_64 0
		.amdhsa_float_denorm_mode_32 3
		.amdhsa_float_denorm_mode_16_64 3
		.amdhsa_dx10_clamp 1
		.amdhsa_ieee_mode 1
		.amdhsa_fp16_overflow 0
		.amdhsa_tg_split 0
		.amdhsa_exception_fp_ieee_invalid_op 0
		.amdhsa_exception_fp_denorm_src 0
		.amdhsa_exception_fp_ieee_div_zero 0
		.amdhsa_exception_fp_ieee_overflow 0
		.amdhsa_exception_fp_ieee_underflow 0
		.amdhsa_exception_fp_ieee_inexact 0
		.amdhsa_exception_int_div_zero 0
	.end_amdhsa_kernel

amdhsa.kernels:
  - .agpr_count:     0
    .args:
      - .offset:         0
        .size:           176
        .value_kind:     by_value
      - .offset:         176
        .size:           4
        .value_kind:     hidden_block_count_x
      - .offset:         180
        .size:           4
        .value_kind:     hidden_block_count_y
      - .offset:         184
        .size:           4
        .value_kind:     hidden_block_count_z
      - .offset:         188
        .size:           2
        .value_kind:     hidden_group_size_x
      - .offset:         190
        .size:           2
        .value_kind:     hidden_group_size_y
      - .offset:         192
        .size:           2
        .value_kind:     hidden_group_size_z
      - .offset:         194
        .size:           2
        .value_kind:     hidden_remainder_x
      - .offset:         196
        .size:           2
        .value_kind:     hidden_remainder_y
      - .offset:         198
        .size:           2
        .value_kind:     hidden_remainder_z
      - .offset:         216
        .size:           8
        .value_kind:     hidden_global_offset_x
      - .offset:         224
        .size:           8
        .value_kind:     hidden_global_offset_y
      - .offset:         232
        .size:           8
        .value_kind:     hidden_global_offset_z
      - .offset:         240
        .size:           2
        .value_kind:     hidden_grid_dims
      - .offset:         264
        .size:           8
        .value_kind:     hidden_multigrid_sync_arg
    .group_segment_fixed_size: 147472
    .kernarg_segment_align: 8
    .kernarg_segment_size: 432
    .language:       OpenCL C
    .language_version:
      - 2
      - 0
    .max_flat_workgroup_size: 512
    .name:           _Z14fwd_megakernel6Params
    .private_segment_fixed_size: 0
    .sgpr_count:     108
    .sgpr_spill_count: 191
    .symbol:         _Z14fwd_megakernel6Params.kd
    .uniform_work_group_size: 1
    .uses_dynamic_stack: false
    .vgpr_count:     255
    .vgpr_spill_count: 0
    .wavefront_size: 64
